# combine phase: next token row's 8 loads issued in the current row's last chunk (row 0 in a prologue)
# speedup vs baseline: 1.0018x; 1.0018x over previous
.LBB0_566:
	s_or_b64 exec, exec, s[0:1]
	s_waitcnt lgkmcnt(0)
	s_barrier
	v_mbcnt_lo_u32_b32 v0, -1, 0
	v_mbcnt_hi_u32_b32 v0, -1, v0
	s_mov_b64 s[4:5], s[28:29]
	v_and_b32_e32 v0, 63, v0
	s_mov_b64 s[0:1], s[28:29]
	v_lshlrev_b32_e32 v1, 2, v0
	global_load_dword v2, v1, s[62:63]
	global_load_dword v3, v1, s[62:63] offset:256
	global_load_dword v4, v1, s[64:65] offset:256
	global_load_dword v5, v1, s[36:37]
	global_load_dword v6, v1, s[36:37] offset:256
	global_load_dword v7, v1, s[66:67] offset:256
	global_load_dword v8, v1, s[64:65]
	s_nop 0
	global_load_dword v1, v1, s[66:67]
	v_mbcnt_hi_u32_b32 v9, -1, v192
	v_and_b32_e32 v10, 64, v9
	v_xor_b32_e32 v11, 1, v9
	v_add_u32_e32 v10, 64, v10
	v_cmp_lt_i32_e32 vcc, v11, v10
	v_xor_b32_e32 v12, 2, v9
	v_xor_b32_e32 v13, 4, v9
	v_cndmask_b32_e32 v11, v9, v11, vcc
	v_lshlrev_b32_e32 v178, 2, v11
	v_cmp_lt_i32_e32 vcc, v12, v10
	v_xor_b32_e32 v14, 8, v9
	v_xor_b32_e32 v15, 16, v9
	v_xor_b32_e32 v16, 32, v9
	v_readlane_b32 s6, v255, 12
	v_readlane_b32 s7, v255, 13
	s_waitcnt vmcnt(5)
	v_mul_f32_e32 v3, v3, v4
	s_waitcnt vmcnt(2)
	v_mul_f32_e32 v4, v7, v6
	s_waitcnt vmcnt(1)
	v_fmac_f32_e32 v3, v2, v8
	s_waitcnt vmcnt(0)
	v_fmac_f32_e32 v4, v1, v5
	ds_bpermute_b32 v1, v178, v3
	ds_bpermute_b32 v2, v178, v4
	v_cndmask_b32_e32 v5, v9, v12, vcc
	v_lshlrev_b32_e32 v156, 2, v5
	v_cmp_lt_i32_e32 vcc, v13, v10
	s_waitcnt lgkmcnt(1)
	v_add_f32_e32 v1, v3, v1
	s_waitcnt lgkmcnt(0)
	v_add_f32_e32 v2, v4, v2
	ds_bpermute_b32 v3, v156, v1
	ds_bpermute_b32 v4, v156, v2
	v_cndmask_b32_e32 v5, v9, v13, vcc
	v_lshlrev_b32_e32 v157, 2, v5
	v_cmp_lt_i32_e32 vcc, v14, v10
	s_waitcnt lgkmcnt(1)
	v_add_f32_e32 v1, v1, v3
	s_waitcnt lgkmcnt(0)
	v_add_f32_e32 v2, v2, v4
	ds_bpermute_b32 v3, v157, v1
	ds_bpermute_b32 v4, v157, v2
	v_cndmask_b32_e32 v5, v9, v14, vcc
	v_lshlrev_b32_e32 v158, 2, v5
	v_cmp_lt_i32_e32 vcc, v15, v10
	s_waitcnt lgkmcnt(1)
	v_add_f32_e32 v1, v1, v3
	s_waitcnt lgkmcnt(0)
	v_add_f32_e32 v2, v2, v4
	ds_bpermute_b32 v3, v158, v1
	ds_bpermute_b32 v4, v158, v2
	v_cndmask_b32_e32 v5, v9, v15, vcc
	v_lshlrev_b32_e32 v176, 2, v5
	v_cmp_lt_i32_e32 vcc, v16, v10
	s_waitcnt lgkmcnt(1)
	v_add_f32_e32 v1, v1, v3
	s_waitcnt lgkmcnt(0)
	v_add_f32_e32 v2, v2, v4
	ds_bpermute_b32 v3, v176, v1
	ds_bpermute_b32 v5, v176, v2
	v_cndmask_b32_e32 v4, v9, v16, vcc
	v_lshlrev_b32_e32 v177, 2, v4
	s_andn2_b64 vcc, exec, s[6:7]
	s_waitcnt lgkmcnt(1)
	v_add_f32_e32 v4, v1, v3
	s_waitcnt lgkmcnt(0)
	v_add_f32_e32 v2, v2, v5
	ds_bpermute_b32 v5, v177, v4
	ds_bpermute_b32 v3, v177, v2
	v_cndmask_b32_e64 v1, 0, 1, s[6:7]
	v_cmp_ne_u32_e64 s[2:3], 1, v1
	s_nop 1
	v_writelane_b32 v255, s2, 26
	s_nop 1
	v_writelane_b32 v255, s3, 27
	s_cbranch_vccnz .LBB0_569
	v_lshlrev_b32_e32 v1, 5, v0
	v_and_b32_e32 v1, 0x3e0, v1
	global_load_dwordx4 v[6:9], v1, s[38:39]
	global_load_dwordx4 v[10:13], v1, s[38:39] offset:16
	s_waitcnt lgkmcnt(1)
	v_add_f32_e32 v4, v4, v5
	s_mov_b32 s8, 0x3fb8aa3b
	s_waitcnt lgkmcnt(0)
	v_add_f32_e32 v2, v2, v3
	v_mul_f32_e32 v3, 0x3fb8aa3b, v4
	v_mul_f32_e32 v14, 0x3fb8aa3b, v2
	v_fma_f32 v15, v4, s8, -v3
	v_rndne_f32_e32 v16, v3
	v_fma_f32 v17, v2, s8, -v14
	v_rndne_f32_e32 v20, v14
	v_fmac_f32_e32 v15, 0x32a5705f, v4
	v_sub_f32_e32 v3, v3, v16
	v_fmac_f32_e32 v17, 0x32a5705f, v2
	v_sub_f32_e32 v14, v14, v20
	v_add_f32_e32 v3, v3, v15
	v_cvt_i32_f32_e32 v16, v16
	v_add_f32_e32 v14, v14, v17
	v_exp_f32_e32 v3, v3
	v_cvt_i32_f32_e32 v20, v20
	v_exp_f32_e32 v14, v14
	s_mov_b32 s13, 0xc2ce8ed0
	s_add_i32 s6, s84, s86
	v_ldexp_f32 v3, v3, v16
	v_cmp_ngt_f32_e32 vcc, s13, v4
	s_mov_b32 s14, 0x42b17218
	s_ashr_i32 s7, s6, 31
	v_ldexp_f32 v14, v14, v20
	v_cndmask_b32_e32 v3, 0, v3, vcc
	v_cmp_ngt_f32_e32 vcc, s13, v2
	v_mov_b32_e32 v5, 0x7f800000
	s_lshl_b64 s[8:9], s[6:7], 12
	v_cndmask_b32_e32 v14, 0, v14, vcc
	v_cmp_nlt_f32_e32 vcc, s14, v4
	s_add_u32 s4, s4, s8
	s_addc_u32 s5, s5, s9
	v_cndmask_b32_e32 v3, v5, v3, vcc
	v_cmp_nlt_f32_e32 vcc, s14, v2
	s_ashr_i32 s23, s22, 31
	s_lshl_b64 s[6:7], s[22:23], 12
	v_cndmask_b32_e32 v2, v5, v14, vcc
	v_sub_f32_e32 v2, v3, v2
	s_mov_b32 s10, 0x3f4ccccd
	s_movk_i32 s11, 0x7fff
	s_add_u32 s8, s0, s8
	v_add_f32_e32 v2, 0x3e4ccccd, v2
	v_mov_b32_e32 v1, 0
	v_lshlrev_b32_e32 v0, 4, v0
	s_mov_b32 s2, 0xffff0000
	v_mov_b32_e32 v18, 0x3727c5ac
	s_mov_b32 s3, 0xf800000
	v_mov_b32_e32 v19, 0x260
	s_mov_b32 s12, 0x34800000
	s_addc_u32 s9, s1, s9
	v_mov_b32_e32 v3, v2
	s_waitcnt vmcnt(1)
	v_mov_b32_e32 v4, v6
	v_mov_b32_e32 v5, v8
	v_mov_b32_e32 v8, v7
	s_waitcnt vmcnt(0)
	v_mov_b32_e32 v14, v10
	v_mov_b32_e32 v15, v12
	v_mov_b32_e32 v12, v11
	v_pk_mul_f32 v[4:5], v[4:5], s[10:11] op_sel_hi:[1,0]
	v_pk_mul_f32 v[6:7], v[8:9], s[10:11] op_sel_hi:[1,0]
	v_pk_mul_f32 v[8:9], v[14:15], s[10:11] op_sel_hi:[1,0]
	v_pk_mul_f32 v[10:11], v[12:13], s[10:11] op_sel_hi:[1,0]
	s_mov_b32 s10, s33
	s_mov_b32 s14, 0x24800000
	s_mov_b32 s15, 0
	s_mov_b32 s18, 0x2c800000
	s_mov_b32 s19, 0
	v_lshl_add_u64 v[70:71], s[4:5], 0, v[0:1]
	v_lshl_add_u64 v[68:69], v[70:71], 0, s[14:15]
	v_lshl_add_u64 v[70:71], v[70:71], 0, s[18:19]
	global_load_dwordx4 v[60:63], v[68:69], off
	global_load_dwordx4 v[64:67], v[70:71], off
	global_load_dwordx4 v[36:39], v[68:69], off offset:1024
	global_load_dwordx4 v[40:43], v[70:71], off offset:1024
	global_load_dwordx4 v[44:47], v[68:69], off offset:2048
	global_load_dwordx4 v[48:51], v[70:71], off offset:2048
	global_load_dwordx4 v[52:55], v[68:69], off offset:3072
	global_load_dwordx4 v[56:59], v[70:71], off offset:3072
	s_waitcnt vmcnt(0)
.LBB0_568:
	s_nop 0
	v_lshl_add_u64 v[12:13], s[8:9], 0, v[0:1]
	s_add_i32 s10, s10, s22
	s_nop 0
	v_add_co_u32_e64 v12, s[0:1], s12, v12
	s_add_u32 s4, s4, s6
	s_addc_u32 s5, s5, s7
	v_addc_co_u32_e64 v13, s[0:1], 0, v13, s[0:1]
	s_add_u32 s8, s8, s6
	s_addc_u32 s9, s9, s7
	s_cmp_lt_i32 s10, 0x8000
	s_waitcnt vmcnt(7)
	v_mov_b32_e32 v20, v60
	v_mov_b32_e32 v21, v61
	v_mov_b32_e32 v22, v62
	v_mov_b32_e32 v23, v63
	v_mov_b32_e32 v24, v64
	v_mov_b32_e32 v25, v65
	v_mov_b32_e32 v26, v66
	v_mov_b32_e32 v27, v67
	v_lshlrev_b32_e32 v29, 16, v21
	v_lshlrev_b32_e32 v28, 16, v20
	v_and_b32_e32 v21, 0xffff0000, v21
	v_lshlrev_b32_e32 v33, 16, v25
	v_lshlrev_b32_e32 v32, 16, v24
	v_and_b32_e32 v20, 0xffff0000, v20
	v_lshlrev_b32_e32 v31, 16, v23
	v_lshlrev_b32_e32 v30, 16, v22
	v_and_b32_e32 v23, 0xffff0000, v23
	v_and_b32_e32 v22, 0xffff0000, v22
	v_and_b32_e32 v25, 0xffff0000, v25
	v_and_b32_e32 v24, 0xffff0000, v24
	v_lshlrev_b32_e32 v35, 16, v27
	v_lshlrev_b32_e32 v34, 16, v26
	v_and_b32_e32 v27, 0xffff0000, v27
	v_and_b32_e32 v26, 0xffff0000, v26
	v_pk_fma_f32 v[28:29], v[2:3], v[32:33], v[28:29] neg_lo:[1,0,0] neg_hi:[1,0,0]
	v_pk_fma_f32 v[20:21], v[2:3], v[24:25], v[20:21] neg_lo:[1,0,0] neg_hi:[1,0,0]
	v_pk_fma_f32 v[24:25], v[2:3], v[34:35], v[30:31] neg_lo:[1,0,0] neg_hi:[1,0,0]
	v_pk_fma_f32 v[22:23], v[2:3], v[26:27], v[22:23] neg_lo:[1,0,0] neg_hi:[1,0,0]
	v_pk_mul_f32 v[26:27], v[28:29], v[28:29]
	v_pk_mul_f32 v[30:31], v[24:25], v[24:25]
	v_pk_fma_f32 v[26:27], v[20:21], v[20:21], v[26:27]
	v_pk_fma_f32 v[30:31], v[22:23], v[22:23], v[30:31]
	v_add_f32_e32 v26, v26, v27
	v_add_f32_e32 v26, v30, v26
	v_add_f32_e32 v26, v31, v26
	ds_bpermute_b32 v27, v178, v26
	s_waitcnt lgkmcnt(0)
	v_add_f32_e32 v26, v26, v27
	ds_bpermute_b32 v27, v156, v26
	s_waitcnt lgkmcnt(0)
	v_add_f32_e32 v26, v26, v27
	ds_bpermute_b32 v27, v157, v26
	s_waitcnt lgkmcnt(0)
	v_add_f32_e32 v26, v26, v27
	ds_bpermute_b32 v27, v158, v26
	s_waitcnt lgkmcnt(0)
	v_add_f32_e32 v26, v26, v27
	ds_bpermute_b32 v27, v176, v26
	s_waitcnt lgkmcnt(0)
	v_add_f32_e32 v26, v26, v27
	v_fmamk_f32 v26, v26, 0x3b800000, v18
	v_mul_f32_e32 v27, 0x4f800000, v26
	v_cmp_gt_f32_e32 vcc, s3, v26
	s_nop 1
	v_cndmask_b32_e32 v26, v26, v27, vcc
	v_sqrt_f32_e32 v27, v26
	s_nop 0
	v_add_u32_e32 v30, -1, v27
	v_add_u32_e32 v31, 1, v27
	v_fma_f32 v32, -v30, v27, v26
	v_fma_f32 v33, -v31, v27, v26
	v_cmp_ge_f32_e64 s[0:1], 0, v32
	s_nop 1
	v_cndmask_b32_e64 v27, v27, v30, s[0:1]
	v_cmp_lt_f32_e64 s[0:1], 0, v33
	s_nop 1
	v_cndmask_b32_e64 v27, v27, v31, s[0:1]
	v_mul_f32_e32 v30, 0x37800000, v27
	v_cndmask_b32_e32 v27, v27, v30, vcc
	v_cmp_class_f32_e32 vcc, v26, v19
	s_nop 1
	v_cndmask_b32_e32 v26, v27, v26, vcc
	v_div_scale_f32 v27, s[0:1], v26, v26, 1.0
	v_rcp_f32_e32 v31, v27
	v_div_scale_f32 v30, vcc, 1.0, v26, 1.0
	v_fma_f32 v32, -v27, v31, 1.0
	v_fmac_f32_e32 v31, v32, v31
	v_mul_f32_e32 v32, v30, v31
	v_fma_f32 v33, -v27, v32, v30
	v_fmac_f32_e32 v32, v33, v31
	v_fma_f32 v27, -v27, v32, v30
	v_div_fmas_f32 v27, v27, v31, v32
	v_div_fixup_f32 v26, v27, v26, 1.0
	v_pk_mul_f32 v[28:29], v[28:29], v[26:27] op_sel_hi:[1,0]
	v_pk_mul_f32 v[24:25], v[24:25], v[26:27] op_sel_hi:[1,0]
	v_pk_mul_f32 v[20:21], v[20:21], v[26:27] op_sel_hi:[1,0]
	v_pk_mul_f32 v[22:23], v[22:23], v[26:27] op_sel_hi:[1,0]
	v_pk_mul_f32 v[26:27], v[4:5], v[28:29]
	v_pk_mul_f32 v[24:25], v[8:9], v[24:25]
	v_pk_mul_f32 v[20:21], v[6:7], v[20:21]
	v_pk_mul_f32 v[22:23], v[10:11], v[22:23]
	v_bfe_u32 v32, v26, 16, 1
	v_bfe_u32 v33, v27, 16, 1
	v_bfe_u32 v34, v24, 16, 1
	v_bfe_u32 v35, v25, 16, 1
	v_bfe_u32 v28, v23, 16, 1
	v_bfe_u32 v29, v22, 16, 1
	v_bfe_u32 v30, v21, 16, 1
	v_bfe_u32 v31, v20, 16, 1
	v_add3_u32 v25, v25, v35, s11
	v_add3_u32 v24, v24, v34, s11
	v_add3_u32 v27, v27, v33, s11
	v_add3_u32 v26, v26, v32, s11
	v_add3_u32 v20, v20, v31, s11
	v_add3_u32 v21, v21, v30, s11
	v_add3_u32 v22, v22, v29, s11
	v_add3_u32 v23, v23, v28, s11
	v_lshrrev_b32_e32 v26, 16, v26
	v_lshrrev_b32_e32 v27, 16, v27
	v_lshrrev_b32_e32 v24, 16, v24
	v_lshrrev_b32_e32 v25, 16, v25
	v_and_or_b32 v23, v23, s2, v25
	v_and_or_b32 v22, v22, s2, v24
	v_and_or_b32 v21, v21, s2, v27
	v_and_or_b32 v20, v20, s2, v26
	global_store_dwordx4 v[12:13], v[20:23], off
	s_waitcnt vmcnt(6)
	s_nop 1
	v_mov_b32_e32 v20, v36
	v_mov_b32_e32 v21, v37
	v_mov_b32_e32 v22, v38
	v_mov_b32_e32 v23, v39
	v_mov_b32_e32 v24, v40
	v_mov_b32_e32 v25, v41
	v_mov_b32_e32 v26, v42
	v_mov_b32_e32 v27, v43
	v_lshlrev_b32_e32 v29, 16, v21
	v_lshlrev_b32_e32 v28, 16, v20
	v_lshlrev_b32_e32 v31, 16, v25
	v_lshlrev_b32_e32 v30, 16, v24
	v_and_b32_e32 v21, 0xffff0000, v21
	v_and_b32_e32 v20, 0xffff0000, v20
	v_and_b32_e32 v25, 0xffff0000, v25
	v_and_b32_e32 v24, 0xffff0000, v24
	v_lshlrev_b32_e32 v33, 16, v23
	v_lshlrev_b32_e32 v32, 16, v22
	v_lshlrev_b32_e32 v35, 16, v27
	v_lshlrev_b32_e32 v34, 16, v26
	v_and_b32_e32 v23, 0xffff0000, v23
	v_and_b32_e32 v22, 0xffff0000, v22
	v_and_b32_e32 v27, 0xffff0000, v27
	v_and_b32_e32 v26, 0xffff0000, v26
	v_pk_fma_f32 v[28:29], v[2:3], v[30:31], v[28:29] neg_lo:[1,0,0] neg_hi:[1,0,0]
	v_pk_fma_f32 v[20:21], v[2:3], v[24:25], v[20:21] neg_lo:[1,0,0] neg_hi:[1,0,0]
	v_pk_fma_f32 v[24:25], v[2:3], v[34:35], v[32:33] neg_lo:[1,0,0] neg_hi:[1,0,0]
	v_pk_fma_f32 v[22:23], v[2:3], v[26:27], v[22:23] neg_lo:[1,0,0] neg_hi:[1,0,0]
	v_pk_mul_f32 v[26:27], v[28:29], v[28:29]
	v_pk_mul_f32 v[30:31], v[24:25], v[24:25]
	v_pk_fma_f32 v[26:27], v[20:21], v[20:21], v[26:27]
	v_pk_fma_f32 v[30:31], v[22:23], v[22:23], v[30:31]
	v_add_f32_e32 v26, v26, v27
	v_add_f32_e32 v26, v30, v26
	v_add_f32_e32 v26, v31, v26
	ds_bpermute_b32 v27, v178, v26
	s_waitcnt lgkmcnt(0)
	v_add_f32_e32 v26, v26, v27
	ds_bpermute_b32 v27, v156, v26
	s_waitcnt lgkmcnt(0)
	v_add_f32_e32 v26, v26, v27
	ds_bpermute_b32 v27, v157, v26
	s_waitcnt lgkmcnt(0)
	v_add_f32_e32 v26, v26, v27
	ds_bpermute_b32 v27, v158, v26
	s_waitcnt lgkmcnt(0)
	v_add_f32_e32 v26, v26, v27
	ds_bpermute_b32 v27, v176, v26
	s_waitcnt lgkmcnt(0)
	v_add_f32_e32 v26, v26, v27
	v_fmamk_f32 v26, v26, 0x3b800000, v18
	v_mul_f32_e32 v27, 0x4f800000, v26
	v_cmp_gt_f32_e32 vcc, s3, v26
	s_nop 1
	v_cndmask_b32_e32 v26, v26, v27, vcc
	v_sqrt_f32_e32 v27, v26
	s_nop 0
	v_add_u32_e32 v30, -1, v27
	v_add_u32_e32 v31, 1, v27
	v_fma_f32 v32, -v30, v27, v26
	v_fma_f32 v33, -v31, v27, v26
	v_cmp_ge_f32_e64 s[0:1], 0, v32
	s_nop 1
	v_cndmask_b32_e64 v27, v27, v30, s[0:1]
	v_cmp_lt_f32_e64 s[0:1], 0, v33
	s_nop 1
	v_cndmask_b32_e64 v27, v27, v31, s[0:1]
	v_mul_f32_e32 v30, 0x37800000, v27
	v_cndmask_b32_e32 v27, v27, v30, vcc
	v_cmp_class_f32_e32 vcc, v26, v19
	s_nop 1
	v_cndmask_b32_e32 v26, v27, v26, vcc
	v_div_scale_f32 v27, s[0:1], v26, v26, 1.0
	v_rcp_f32_e32 v31, v27
	v_div_scale_f32 v30, vcc, 1.0, v26, 1.0
	v_fma_f32 v32, -v27, v31, 1.0
	v_fmac_f32_e32 v31, v32, v31
	v_mul_f32_e32 v32, v30, v31
	v_fma_f32 v33, -v27, v32, v30
	v_fmac_f32_e32 v32, v33, v31
	v_fma_f32 v27, -v27, v32, v30
	v_div_fmas_f32 v27, v27, v31, v32
	v_div_fixup_f32 v26, v27, v26, 1.0
	v_pk_mul_f32 v[28:29], v[28:29], v[26:27] op_sel_hi:[1,0]
	v_pk_mul_f32 v[24:25], v[24:25], v[26:27] op_sel_hi:[1,0]
	v_pk_mul_f32 v[20:21], v[20:21], v[26:27] op_sel_hi:[1,0]
	v_pk_mul_f32 v[22:23], v[22:23], v[26:27] op_sel_hi:[1,0]
	v_pk_mul_f32 v[26:27], v[4:5], v[28:29]
	v_pk_mul_f32 v[24:25], v[8:9], v[24:25]
	v_pk_mul_f32 v[20:21], v[6:7], v[20:21]
	v_pk_mul_f32 v[22:23], v[10:11], v[22:23]
	v_bfe_u32 v32, v26, 16, 1
	v_bfe_u32 v33, v27, 16, 1
	v_bfe_u32 v34, v24, 16, 1
	v_bfe_u32 v35, v25, 16, 1
	v_bfe_u32 v28, v23, 16, 1
	v_bfe_u32 v29, v22, 16, 1
	v_bfe_u32 v30, v21, 16, 1
	v_bfe_u32 v31, v20, 16, 1
	v_add3_u32 v25, v25, v35, s11
	v_add3_u32 v24, v24, v34, s11
	v_add3_u32 v27, v27, v33, s11
	v_add3_u32 v26, v26, v32, s11
	v_add3_u32 v20, v20, v31, s11
	v_add3_u32 v21, v21, v30, s11
	v_add3_u32 v22, v22, v29, s11
	v_add3_u32 v23, v23, v28, s11
	v_lshrrev_b32_e32 v26, 16, v26
	v_lshrrev_b32_e32 v27, 16, v27
	v_lshrrev_b32_e32 v24, 16, v24
	v_lshrrev_b32_e32 v25, 16, v25
	v_and_or_b32 v23, v23, s2, v25
	v_and_or_b32 v22, v22, s2, v24
	v_and_or_b32 v21, v21, s2, v27
	v_and_or_b32 v20, v20, s2, v26
	global_store_dwordx4 v[12:13], v[20:23], off offset:1024
	s_waitcnt vmcnt(5)
	s_nop 1
	v_mov_b32_e32 v20, v44
	v_mov_b32_e32 v21, v45
	v_mov_b32_e32 v22, v46
	v_mov_b32_e32 v23, v47
	v_mov_b32_e32 v24, v48
	v_mov_b32_e32 v25, v49
	v_mov_b32_e32 v26, v50
	v_mov_b32_e32 v27, v51
	v_lshlrev_b32_e32 v29, 16, v21
	v_lshlrev_b32_e32 v28, 16, v20
	v_lshlrev_b32_e32 v31, 16, v25
	v_lshlrev_b32_e32 v30, 16, v24
	v_and_b32_e32 v21, 0xffff0000, v21
	v_and_b32_e32 v20, 0xffff0000, v20
	v_and_b32_e32 v25, 0xffff0000, v25
	v_and_b32_e32 v24, 0xffff0000, v24
	v_lshlrev_b32_e32 v33, 16, v23
	v_lshlrev_b32_e32 v32, 16, v22
	v_lshlrev_b32_e32 v35, 16, v27
	v_lshlrev_b32_e32 v34, 16, v26
	v_and_b32_e32 v23, 0xffff0000, v23
	v_and_b32_e32 v22, 0xffff0000, v22
	v_and_b32_e32 v27, 0xffff0000, v27
	v_and_b32_e32 v26, 0xffff0000, v26
	v_pk_fma_f32 v[28:29], v[2:3], v[30:31], v[28:29] neg_lo:[1,0,0] neg_hi:[1,0,0]
	v_pk_fma_f32 v[20:21], v[2:3], v[24:25], v[20:21] neg_lo:[1,0,0] neg_hi:[1,0,0]
	v_pk_fma_f32 v[24:25], v[2:3], v[34:35], v[32:33] neg_lo:[1,0,0] neg_hi:[1,0,0]
	v_pk_fma_f32 v[22:23], v[2:3], v[26:27], v[22:23] neg_lo:[1,0,0] neg_hi:[1,0,0]
	v_pk_mul_f32 v[26:27], v[28:29], v[28:29]
	v_pk_mul_f32 v[30:31], v[24:25], v[24:25]
	v_pk_fma_f32 v[26:27], v[20:21], v[20:21], v[26:27]
	v_pk_fma_f32 v[30:31], v[22:23], v[22:23], v[30:31]
	v_add_f32_e32 v26, v26, v27
	v_add_f32_e32 v26, v30, v26
	v_add_f32_e32 v26, v31, v26
	ds_bpermute_b32 v27, v178, v26
	s_waitcnt lgkmcnt(0)
	v_add_f32_e32 v26, v26, v27
	ds_bpermute_b32 v27, v156, v26
	s_waitcnt lgkmcnt(0)
	v_add_f32_e32 v26, v26, v27
	ds_bpermute_b32 v27, v157, v26
	s_waitcnt lgkmcnt(0)
	v_add_f32_e32 v26, v26, v27
	ds_bpermute_b32 v27, v158, v26
	s_waitcnt lgkmcnt(0)
	v_add_f32_e32 v26, v26, v27
	ds_bpermute_b32 v27, v176, v26
	s_waitcnt lgkmcnt(0)
	v_add_f32_e32 v26, v26, v27
	v_fmamk_f32 v26, v26, 0x3b800000, v18
	v_mul_f32_e32 v27, 0x4f800000, v26
	v_cmp_gt_f32_e32 vcc, s3, v26
	s_nop 1
	v_cndmask_b32_e32 v26, v26, v27, vcc
	v_sqrt_f32_e32 v27, v26
	s_nop 0
	v_add_u32_e32 v30, -1, v27
	v_add_u32_e32 v31, 1, v27
	v_fma_f32 v32, -v30, v27, v26
	v_fma_f32 v33, -v31, v27, v26
	v_cmp_ge_f32_e64 s[0:1], 0, v32
	s_nop 1
	v_cndmask_b32_e64 v27, v27, v30, s[0:1]
	v_cmp_lt_f32_e64 s[0:1], 0, v33
	s_nop 1
	v_cndmask_b32_e64 v27, v27, v31, s[0:1]
	v_mul_f32_e32 v30, 0x37800000, v27
	v_cndmask_b32_e32 v27, v27, v30, vcc
	v_cmp_class_f32_e32 vcc, v26, v19
	s_nop 1
	v_cndmask_b32_e32 v26, v27, v26, vcc
	v_div_scale_f32 v27, s[0:1], v26, v26, 1.0
	v_rcp_f32_e32 v31, v27
	v_div_scale_f32 v30, vcc, 1.0, v26, 1.0
	v_fma_f32 v32, -v27, v31, 1.0
	v_fmac_f32_e32 v31, v32, v31
	v_mul_f32_e32 v32, v30, v31
	v_fma_f32 v33, -v27, v32, v30
	v_fmac_f32_e32 v32, v33, v31
	v_fma_f32 v27, -v27, v32, v30
	v_div_fmas_f32 v27, v27, v31, v32
	v_div_fixup_f32 v26, v27, v26, 1.0
	v_pk_mul_f32 v[28:29], v[28:29], v[26:27] op_sel_hi:[1,0]
	v_pk_mul_f32 v[24:25], v[24:25], v[26:27] op_sel_hi:[1,0]
	v_pk_mul_f32 v[20:21], v[20:21], v[26:27] op_sel_hi:[1,0]
	v_pk_mul_f32 v[22:23], v[22:23], v[26:27] op_sel_hi:[1,0]
	v_pk_mul_f32 v[26:27], v[4:5], v[28:29]
	v_pk_mul_f32 v[24:25], v[8:9], v[24:25]
	v_pk_mul_f32 v[20:21], v[6:7], v[20:21]
	v_pk_mul_f32 v[22:23], v[10:11], v[22:23]
	v_bfe_u32 v32, v26, 16, 1
	v_bfe_u32 v33, v27, 16, 1
	v_bfe_u32 v34, v24, 16, 1
	v_bfe_u32 v35, v25, 16, 1
	v_bfe_u32 v28, v23, 16, 1
	v_bfe_u32 v29, v22, 16, 1
	v_bfe_u32 v30, v21, 16, 1
	v_bfe_u32 v31, v20, 16, 1
	v_add3_u32 v25, v25, v35, s11
	v_add3_u32 v24, v24, v34, s11
	v_add3_u32 v27, v27, v33, s11
	v_add3_u32 v26, v26, v32, s11
	v_add3_u32 v20, v20, v31, s11
	v_add3_u32 v21, v21, v30, s11
	v_add3_u32 v22, v22, v29, s11
	v_add3_u32 v23, v23, v28, s11
	v_lshrrev_b32_e32 v26, 16, v26
	v_lshrrev_b32_e32 v27, 16, v27
	v_lshrrev_b32_e32 v24, 16, v24
	v_lshrrev_b32_e32 v25, 16, v25
	v_and_or_b32 v23, v23, s2, v25
	v_and_or_b32 v22, v22, s2, v24
	v_and_or_b32 v21, v21, s2, v27
	v_and_or_b32 v20, v20, s2, v26
	global_store_dwordx4 v[12:13], v[20:23], off offset:2048
	s_waitcnt vmcnt(4)
	s_nop 1
	v_mov_b32_e32 v20, v52
	v_mov_b32_e32 v21, v53
	v_mov_b32_e32 v22, v54
	v_mov_b32_e32 v23, v55
	v_mov_b32_e32 v14, v56
	v_mov_b32_e32 v15, v57
	v_mov_b32_e32 v16, v58
	v_mov_b32_e32 v17, v59
	v_lshl_add_u64 v[70:71], s[4:5], 0, v[0:1]
	v_lshl_add_u64 v[68:69], v[70:71], 0, s[14:15]
	v_lshl_add_u64 v[70:71], v[70:71], 0, s[18:19]
	global_load_dwordx4 v[60:63], v[68:69], off
	global_load_dwordx4 v[64:67], v[70:71], off
	global_load_dwordx4 v[36:39], v[68:69], off offset:1024
	global_load_dwordx4 v[40:43], v[70:71], off offset:1024
	global_load_dwordx4 v[44:47], v[68:69], off offset:2048
	global_load_dwordx4 v[48:51], v[70:71], off offset:2048
	global_load_dwordx4 v[52:55], v[68:69], off offset:3072
	global_load_dwordx4 v[56:59], v[70:71], off offset:3072
	v_lshlrev_b32_e32 v25, 16, v21
	v_lshlrev_b32_e32 v24, 16, v20
	v_lshlrev_b32_e32 v27, 16, v15
	v_lshlrev_b32_e32 v26, 16, v14
	v_and_b32_e32 v21, 0xffff0000, v21
	v_and_b32_e32 v20, 0xffff0000, v20
	v_and_b32_e32 v15, 0xffff0000, v15
	v_and_b32_e32 v14, 0xffff0000, v14
	v_lshlrev_b32_e32 v29, 16, v23
	v_lshlrev_b32_e32 v28, 16, v22
	v_lshlrev_b32_e32 v31, 16, v17
	v_lshlrev_b32_e32 v30, 16, v16
	v_and_b32_e32 v23, 0xffff0000, v23
	v_and_b32_e32 v22, 0xffff0000, v22
	v_and_b32_e32 v17, 0xffff0000, v17
	v_and_b32_e32 v16, 0xffff0000, v16
	v_pk_fma_f32 v[24:25], v[2:3], v[26:27], v[24:25] neg_lo:[1,0,0] neg_hi:[1,0,0]
	v_pk_fma_f32 v[14:15], v[2:3], v[14:15], v[20:21] neg_lo:[1,0,0] neg_hi:[1,0,0]
	v_pk_fma_f32 v[20:21], v[2:3], v[30:31], v[28:29] neg_lo:[1,0,0] neg_hi:[1,0,0]
	v_pk_fma_f32 v[16:17], v[2:3], v[16:17], v[22:23] neg_lo:[1,0,0] neg_hi:[1,0,0]
	v_pk_mul_f32 v[22:23], v[24:25], v[24:25]
	v_pk_mul_f32 v[26:27], v[20:21], v[20:21]
	v_pk_fma_f32 v[22:23], v[14:15], v[14:15], v[22:23]
	v_pk_fma_f32 v[26:27], v[16:17], v[16:17], v[26:27]
	v_add_f32_e32 v22, v22, v23
	v_add_f32_e32 v22, v26, v22
	v_add_f32_e32 v22, v27, v22
	ds_bpermute_b32 v23, v178, v22
	s_waitcnt lgkmcnt(0)
	v_add_f32_e32 v22, v22, v23
	ds_bpermute_b32 v23, v156, v22
	s_waitcnt lgkmcnt(0)
	v_add_f32_e32 v22, v22, v23
	ds_bpermute_b32 v23, v157, v22
	s_waitcnt lgkmcnt(0)
	v_add_f32_e32 v22, v22, v23
	ds_bpermute_b32 v23, v158, v22
	s_waitcnt lgkmcnt(0)
	v_add_f32_e32 v22, v22, v23
	ds_bpermute_b32 v23, v176, v22
	s_waitcnt lgkmcnt(0)
	v_add_f32_e32 v22, v22, v23
	v_fmamk_f32 v22, v22, 0x3b800000, v18
	v_mul_f32_e32 v23, 0x4f800000, v22
	v_cmp_gt_f32_e32 vcc, s3, v22
	s_nop 1
	v_cndmask_b32_e32 v22, v22, v23, vcc
	v_sqrt_f32_e32 v23, v22
	s_nop 0
	v_add_u32_e32 v26, -1, v23
	v_add_u32_e32 v27, 1, v23
	v_fma_f32 v28, -v26, v23, v22
	v_fma_f32 v29, -v27, v23, v22
	v_cmp_ge_f32_e64 s[0:1], 0, v28
	s_nop 1
	v_cndmask_b32_e64 v23, v23, v26, s[0:1]
	v_cmp_lt_f32_e64 s[0:1], 0, v29
	s_nop 1
	v_cndmask_b32_e64 v23, v23, v27, s[0:1]
	v_mul_f32_e32 v26, 0x37800000, v23
	v_cndmask_b32_e32 v23, v23, v26, vcc
	v_cmp_class_f32_e32 vcc, v22, v19
	s_nop 1
	v_cndmask_b32_e32 v22, v23, v22, vcc
	v_div_scale_f32 v23, s[0:1], v22, v22, 1.0
	v_rcp_f32_e32 v27, v23
	v_div_scale_f32 v26, vcc, 1.0, v22, 1.0
	v_fma_f32 v28, -v23, v27, 1.0
	v_fmac_f32_e32 v27, v28, v27
	v_mul_f32_e32 v28, v26, v27
	v_fma_f32 v29, -v23, v28, v26
	v_fmac_f32_e32 v28, v29, v27
	v_fma_f32 v23, -v23, v28, v26
	v_div_fmas_f32 v23, v23, v27, v28
	v_div_fixup_f32 v22, v23, v22, 1.0
	v_pk_mul_f32 v[24:25], v[24:25], v[22:23] op_sel_hi:[1,0]
	v_pk_mul_f32 v[20:21], v[20:21], v[22:23] op_sel_hi:[1,0]
	v_pk_mul_f32 v[14:15], v[14:15], v[22:23] op_sel_hi:[1,0]
	v_pk_mul_f32 v[16:17], v[16:17], v[22:23] op_sel_hi:[1,0]
	v_pk_mul_f32 v[22:23], v[4:5], v[24:25]
	v_pk_mul_f32 v[20:21], v[8:9], v[20:21]
	v_pk_mul_f32 v[14:15], v[6:7], v[14:15]
	v_pk_mul_f32 v[16:17], v[10:11], v[16:17]
	v_bfe_u32 v28, v22, 16, 1
	v_bfe_u32 v29, v23, 16, 1
	v_bfe_u32 v30, v20, 16, 1
	v_bfe_u32 v31, v21, 16, 1
	v_bfe_u32 v24, v17, 16, 1
	v_bfe_u32 v25, v16, 16, 1
	v_bfe_u32 v26, v15, 16, 1
	v_bfe_u32 v27, v14, 16, 1
	v_add3_u32 v21, v21, v31, s11
	v_add3_u32 v20, v20, v30, s11
	v_add3_u32 v23, v23, v29, s11
	v_add3_u32 v22, v22, v28, s11
	v_add3_u32 v14, v14, v27, s11
	v_add3_u32 v15, v15, v26, s11
	v_add3_u32 v16, v16, v25, s11
	v_add3_u32 v17, v17, v24, s11
	v_lshrrev_b32_e32 v22, 16, v22
	v_lshrrev_b32_e32 v23, 16, v23
	v_lshrrev_b32_e32 v20, 16, v20
	v_lshrrev_b32_e32 v21, 16, v21
	v_and_or_b32 v17, v17, s2, v21
	v_and_or_b32 v16, v16, s2, v20
	v_and_or_b32 v15, v15, s2, v23
	v_and_or_b32 v14, v14, s2, v22
	global_store_dwordx4 v[12:13], v[14:17], off offset:3072
	s_cbranch_scc1 .LBB0_568
